# scan step loop: next chunk's K and V register loads issued right after the step's first barrier (destination registers idle during part 1)
# speedup vs baseline: 1.0061x; 1.0061x over previous
.LBB0_628:
	s_bitcmp1_b32 s57, 0
	s_cselect_b32 s50, 0x900, 0
	s_add_i32 s61, s50, 0
	s_add_i32 s61, s61, 0x1c800
	s_waitcnt vmcnt(8)
	ds_write_b128 v184, v[4:7]
	s_waitcnt vmcnt(7)
	ds_write_b128 v185, v[8:11]
	s_waitcnt vmcnt(6)
	ds_write_b128 v186, v[12:15]
	s_waitcnt vmcnt(5)
	ds_write_b128 v187, v[16:19]
	s_waitcnt vmcnt(4)
	ds_write_b128 v188, v[20:23]
	s_waitcnt vmcnt(3)
	ds_write_b128 v189, v[24:27]
	s_waitcnt vmcnt(2)
	ds_write_b128 v190, v[28:31]
	s_waitcnt vmcnt(1)
	ds_write_b128 v191, v[32:35]
	v_lshl_add_u32 v1, v160, 2, s61
	ds_read_b32 v2, v1 offset:1536
	s_waitcnt vmcnt(0)
	v_lshlrev_b32_e32 v96, 16, v36
	v_and_b32_e32 v97, 0xffff0000, v36
	ds_write_b16 v165, v36
	ds_write_b16_d16_hi v165, v36 offset:272
	ds_write_b16 v165, v37 offset:544
	ds_write_b16_d16_hi v165, v37 offset:816
	ds_write_b16 v165, v38 offset:1088
	ds_write_b16_d16_hi v165, v38 offset:1360
	ds_write_b16 v165, v39 offset:1632
	ds_write_b16_d16_hi v165, v39 offset:1904
	s_waitcnt lgkmcnt(8)
	v_pk_mul_f32 v[96:97], v[2:3], v[96:97] op_sel_hi:[0,1]
	v_cvt_pk_bf16_f32 v1, v96, v97
	v_lshlrev_b32_e32 v96, 16, v37
	v_and_b32_e32 v97, 0xffff0000, v37
	v_pk_mul_f32 v[96:97], v[2:3], v[96:97] op_sel_hi:[0,1]
	v_cvt_pk_bf16_f32 v3, v96, v97
	v_lshlrev_b32_e32 v96, 16, v38
	v_and_b32_e32 v97, 0xffff0000, v38
	v_pk_mul_f32 v[96:97], v[2:3], v[96:97] op_sel_hi:[0,1]
	v_cvt_pk_bf16_f32 v98, v96, v97
	v_lshlrev_b32_e32 v96, 16, v39
	v_and_b32_e32 v97, 0xffff0000, v39
	v_pk_mul_f32 v[96:97], v[2:3], v[96:97] op_sel_hi:[0,1]
	v_cvt_pk_bf16_f32 v96, v96, v97
	ds_write_b16 v166, v1
	ds_write_b16_d16_hi v166, v1 offset:272
	ds_write_b16 v166, v3 offset:544
	ds_write_b16_d16_hi v166, v3 offset:816
	ds_write_b16 v166, v98 offset:1088
	ds_write_b16_d16_hi v166, v98 offset:1360
	ds_write_b16 v166, v96 offset:1632
	ds_write_b16_d16_hi v166, v96 offset:1904
	s_and_saveexec_b64 s[50:51], s[14:15]
	v_cvt_pk_bf16_f32 v1, v2, s0
	ds_write_b16 v167, v1
	s_or_b64 exec, exec, s[50:51]
	s_cmp_lt_u32 s57, 2
	s_waitcnt lgkmcnt(0)
	s_barrier
	s_cbranch_scc1 .LBB0_655
	s_mov_b32 s99, 0
	s_cmp_eq_u32 s57, 33
	s_cbranch_scc1 .Lscan_kv_early_done
	s_add_i32 s98, s57, -1
	s_and_b64 vcc, s[46:47], exec
	s_cselect_b32 s98, s98, s60
	s_lshl_b32 s98, s98, 7
	s_add_i32 s98, s98, s58
	v_add_u32_e32 v2, s98, v197
	v_add_u32_e32 v4, s98, v198
	v_ashrrev_i32_e32 v3, 31, v2
	v_ashrrev_i32_e32 v5, 31, v4
	v_lshlrev_b64 v[2:3], 11, v[2:3]
	v_lshlrev_b64 v[4:5], 11, v[4:5]
	v_lshl_add_u64 v[2:3], v[148:149], 0, v[2:3]
	v_lshl_add_u64 v[8:9], v[148:149], 0, v[4:5]
	global_load_dwordx4 v[4:7], v[2:3], off
	s_nop 0
	global_load_dwordx4 v[8:11], v[8:9], off
	v_add_u32_e32 v2, s98, v199
	v_add_u32_e32 v12, s98, v200
	v_ashrrev_i32_e32 v3, 31, v2
	v_ashrrev_i32_e32 v13, 31, v12
	v_lshlrev_b64 v[2:3], 11, v[2:3]
	v_lshlrev_b64 v[12:13], 11, v[12:13]
	v_lshl_add_u64 v[2:3], v[148:149], 0, v[2:3]
	v_lshl_add_u64 v[16:17], v[148:149], 0, v[12:13]
	global_load_dwordx4 v[12:15], v[2:3], off
	s_nop 0
	global_load_dwordx4 v[16:19], v[16:17], off
	v_add_u32_e32 v2, s98, v201
	v_add_u32_e32 v20, s98, v202
	v_ashrrev_i32_e32 v3, 31, v2
	v_ashrrev_i32_e32 v21, 31, v20
	v_lshlrev_b64 v[2:3], 11, v[2:3]
	v_lshlrev_b64 v[20:21], 11, v[20:21]
	v_lshl_add_u64 v[2:3], v[148:149], 0, v[2:3]
	v_lshl_add_u64 v[24:25], v[148:149], 0, v[20:21]
	global_load_dwordx4 v[20:23], v[2:3], off
	s_nop 0
	global_load_dwordx4 v[24:27], v[24:25], off
	v_add_u32_e32 v2, s98, v203
	v_add_u32_e32 v28, s98, v204
	v_ashrrev_i32_e32 v3, 31, v2
	v_ashrrev_i32_e32 v29, 31, v28
	v_lshlrev_b64 v[2:3], 11, v[2:3]
	v_lshlrev_b64 v[28:29], 11, v[28:29]
	v_lshl_add_u64 v[2:3], v[148:149], 0, v[2:3]
	v_lshl_add_u64 v[32:33], v[148:149], 0, v[28:29]
	global_load_dwordx4 v[28:31], v[2:3], off
	s_nop 0
	global_load_dwordx4 v[32:35], v[32:33], off
	v_or_b32_e32 v2, s98, v205
	v_ashrrev_i32_e32 v3, 31, v2
	v_lshlrev_b64 v[2:3], 11, v[2:3]
	v_lshl_add_u64 v[2:3], v[154:155], 0, v[2:3]
	global_load_dwordx4 v[36:39], v[2:3], off
	s_mov_b32 s99, 1

.LBB0_655:
	s_mov_b32 s99, 0
	s_cmp_eq_u32 s57, 33
	s_cselect_b64 s[50:51], -1, 0
	s_and_b64 vcc, exec, s[50:51]
	s_cbranch_vccnz .LBB0_678
.LBB0_656:
	v_sub_co_u32_e64 v1, s[54:55], s57, 1
	s_and_b64 s[62:63], s[46:47], exec
	v_readfirstlane_b32 s62, v1
	s_cselect_b32 s62, s62, s60
	s_lshl_b32 s62, s62, 7
	s_add_i32 s62, s62, s58
	s_and_b64 vcc, s[54:55], exec
	s_cselect_b32 s63, s59, s62
	s_cmp_eq_u32 s99, 1
	s_cbranch_scc1 .Lscan_kv_late_skip
	v_add_u32_e32 v2, s63, v197
	v_add_u32_e32 v4, s63, v198
	v_ashrrev_i32_e32 v3, 31, v2
	v_ashrrev_i32_e32 v5, 31, v4
	v_lshlrev_b64 v[2:3], 11, v[2:3]
	v_lshlrev_b64 v[4:5], 11, v[4:5]
	v_lshl_add_u64 v[2:3], v[148:149], 0, v[2:3]
	v_lshl_add_u64 v[8:9], v[148:149], 0, v[4:5]
	global_load_dwordx4 v[4:7], v[2:3], off
	s_nop 0
	global_load_dwordx4 v[8:11], v[8:9], off
	v_add_u32_e32 v2, s63, v199
	v_add_u32_e32 v12, s63, v200
	v_ashrrev_i32_e32 v3, 31, v2
	v_ashrrev_i32_e32 v13, 31, v12
	v_lshlrev_b64 v[2:3], 11, v[2:3]
	v_lshlrev_b64 v[12:13], 11, v[12:13]
	v_lshl_add_u64 v[2:3], v[148:149], 0, v[2:3]
	v_lshl_add_u64 v[16:17], v[148:149], 0, v[12:13]
	global_load_dwordx4 v[12:15], v[2:3], off
	s_nop 0
	global_load_dwordx4 v[16:19], v[16:17], off
	v_add_u32_e32 v2, s63, v201
	v_add_u32_e32 v20, s63, v202
	v_ashrrev_i32_e32 v3, 31, v2
	v_ashrrev_i32_e32 v21, 31, v20
	v_lshlrev_b64 v[2:3], 11, v[2:3]
	v_lshlrev_b64 v[20:21], 11, v[20:21]
	v_lshl_add_u64 v[2:3], v[148:149], 0, v[2:3]
	v_lshl_add_u64 v[24:25], v[148:149], 0, v[20:21]
	global_load_dwordx4 v[20:23], v[2:3], off
	s_nop 0
	global_load_dwordx4 v[24:27], v[24:25], off
	v_add_u32_e32 v2, s63, v203
	v_add_u32_e32 v28, s63, v204
	v_ashrrev_i32_e32 v3, 31, v2
	v_ashrrev_i32_e32 v29, 31, v28
	v_lshlrev_b64 v[2:3], 11, v[2:3]
	v_lshlrev_b64 v[28:29], 11, v[28:29]
	v_lshl_add_u64 v[2:3], v[148:149], 0, v[2:3]
	v_lshl_add_u64 v[32:33], v[148:149], 0, v[28:29]
	global_load_dwordx4 v[28:31], v[2:3], off
	s_nop 0
	global_load_dwordx4 v[32:35], v[32:33], off
	v_or_b32_e32 v2, s63, v205
	v_ashrrev_i32_e32 v3, 31, v2
	v_lshlrev_b64 v[2:3], 11, v[2:3]
	v_lshl_add_u64 v[2:3], v[154:155], 0, v[2:3]
	global_load_dwordx4 v[36:39], v[2:3], off
.Lscan_kv_late_skip:
	s_and_saveexec_b64 vcc, s[10:11]
	s_cbranch_execz .LBB0_658
	v_or_b32_e32 v2, s63, v206
	v_ashrrev_i32_e32 v3, 31, v2
	v_or_b32_e32 v96, s63, v207
	v_lshlrev_b64 v[2:3], 6, v[2:3]
	v_ashrrev_i32_e32 v97, 31, v96
	v_lshl_add_u64 v[2:3], s[52:53], 0, v[2:3]
	v_lshlrev_b64 v[96:97], 6, v[96:97]
	v_lshl_add_u64 v[96:97], s[52:53], 0, v[96:97]
	global_load_dword v150, v[2:3], off
	global_load_dword v208, v[2:3], off offset:16
	global_load_dword v151, v[96:97], off
	global_load_dword v209, v[96:97], off offset:16

	.amdhsa_kernel _Z14fwd_megakernel4Args
		.amdhsa_group_segment_fixed_size 0
		.amdhsa_private_segment_fixed_size 0
		.amdhsa_kernarg_size 472
		.amdhsa_user_sgpr_count 2
		.amdhsa_user_sgpr_dispatch_ptr 0
		.amdhsa_user_sgpr_queue_ptr 0
		.amdhsa_user_sgpr_kernarg_segment_ptr 1
		.amdhsa_user_sgpr_dispatch_id 0
		.amdhsa_user_sgpr_kernarg_preload_length 0
		.amdhsa_user_sgpr_kernarg_preload_offset 0
		.amdhsa_user_sgpr_private_segment_size 0
		.amdhsa_uses_dynamic_stack 0
		.amdhsa_enable_private_segment 0
		.amdhsa_system_sgpr_workgroup_id_x 1
		.amdhsa_system_sgpr_workgroup_id_y 0
		.amdhsa_system_sgpr_workgroup_id_z 0
		.amdhsa_system_sgpr_workgroup_info 0
		.amdhsa_system_vgpr_workitem_id 2
		.amdhsa_next_free_vgpr 256
		.amdhsa_next_free_sgpr 102
		.amdhsa_accum_offset 256
		.amdhsa_reserve_vcc 1
		.amdhsa_float_round_mode_32 0
		.amdhsa_float_round_mode_16_64 0
		.amdhsa_float_denorm_mode_32 3
		.amdhsa_float_denorm_mode_16_64 3
		.amdhsa_dx10_clamp 1
		.amdhsa_ieee_mode 1
		.amdhsa_fp16_overflow 0
		.amdhsa_tg_split 0
		.amdhsa_exception_fp_ieee_invalid_op 0
		.amdhsa_exception_fp_denorm_src 0
		.amdhsa_exception_fp_ieee_div_zero 0
		.amdhsa_exception_fp_ieee_overflow 0
		.amdhsa_exception_fp_ieee_underflow 0
		.amdhsa_exception_fp_ieee_inexact 0
		.amdhsa_exception_int_div_zero 0
	.end_amdhsa_kernel

.Lfunc_end0:
	.size	_Z14fwd_megakernel4Args, .Lfunc_end0-_Z14fwd_megakernel4Args
	.set _Z14fwd_megakernel4Args.num_vgpr, 256
	.set _Z14fwd_megakernel4Args.num_agpr, 0
	.set _Z14fwd_megakernel4Args.numbered_sgpr, 102
	.set _Z14fwd_megakernel4Args.num_named_barrier, 0
	.set _Z14fwd_megakernel4Args.private_seg_size, 0
	.set _Z14fwd_megakernel4Args.uses_vcc, 1
	.set _Z14fwd_megakernel4Args.uses_flat_scratch, 0
	.set _Z14fwd_megakernel4Args.has_dyn_sized_stack, 0
	.set _Z14fwd_megakernel4Args.has_recursion, 0
	.set _Z14fwd_megakernel4Args.has_indirect_call, 0

amdhsa.kernels:
  - .agpr_count:     0
    .args:
      - .offset:         0
        .size:           216
        .value_kind:     by_value
      - .offset:         216
        .size:           4
        .value_kind:     hidden_block_count_x
      - .offset:         220
        .size:           4
        .value_kind:     hidden_block_count_y
      - .offset:         224
        .size:           4
        .value_kind:     hidden_block_count_z
      - .offset:         228
        .size:           2
        .value_kind:     hidden_group_size_x
      - .offset:         230
        .size:           2
        .value_kind:     hidden_group_size_y
      - .offset:         232
        .size:           2
        .value_kind:     hidden_group_size_z
      - .offset:         234
        .size:           2
        .value_kind:     hidden_remainder_x
      - .offset:         236
        .size:           2
        .value_kind:     hidden_remainder_y
      - .offset:         238
        .size:           2
        .value_kind:     hidden_remainder_z
      - .offset:         256
        .size:           8
        .value_kind:     hidden_global_offset_x
      - .offset:         264
        .size:           8
        .value_kind:     hidden_global_offset_y
      - .offset:         272
        .size:           8
        .value_kind:     hidden_global_offset_z
      - .offset:         280
        .size:           2
        .value_kind:     hidden_grid_dims
      - .offset:         304
        .size:           8
        .value_kind:     hidden_multigrid_sync_arg
      - .offset:         336
        .size:           4
        .value_kind:     hidden_dynamic_lds_size
    .group_segment_fixed_size: 0
    .kernarg_segment_align: 8
    .kernarg_segment_size: 472
    .language:       OpenCL C
    .language_version:
      - 2
      - 0
    .max_flat_workgroup_size: 512
    .name:           _Z14fwd_megakernel4Args
    .private_segment_fixed_size: 0
    .sgpr_count:     108
    .sgpr_spill_count: 142
    .symbol:         _Z14fwd_megakernel4Args.kd
    .uniform_work_group_size: 1
    .uses_dynamic_stack: false
    .vgpr_count:     256
    .vgpr_spill_count: 0
    .wavefront_size: 64
